# drop priority flip between PV0 and QK1 MFMA groups; fast-path entry skips redundant setprio
# baseline (speedup 1.0000x reference)
.LBB0_1278:
	s_cmp_le_i32 s35, s89
	s_cselect_b64 s[70:71], -1, 0
	s_cmp_gt_i32 s35, s89
	s_cbranch_scc1 .LBB0_1288
	s_and_b32 vcc_lo, s35, 1
	s_mul_i32 vcc_hi, vcc_lo, 0x4800
	v_add_u32_e32 v237, vcc_hi, v234
	v_add_u32_e32 v217, 0xd000, v237
	s_mulk_i32 vcc_lo, 0x6800
	s_add_i32 vcc_lo, vcc_lo, 0
	s_setprio 1
.Lfh:
	s_waitcnt lgkmcnt(8)
	v_mfma_f32_32x32x16_bf16 v[64:79], v[168:171], v[80:83], v[238:253]
	ds_read_b128 v[180:183], v237 offset:53248
	ds_read_b128 v[176:179], v237 offset:53280
	v_add_u32_e32 v172, vcc_lo, v229
	v_add_u32_e32 v218, vcc_lo, v233
	v_mfma_f32_32x32x16_bf16 v[64:79], v[160:163], v[84:87], v[64:79]
	ds_read_b128 v[196:199], v237 offset:57856
	ds_read_b128 v[188:191], v237 offset:62464
	v_mfma_f32_32x32x16_bf16 v[64:79], v[164:167], v[88:91], v[64:79]
	ds_read_b128 v[200:203], v217 offset:13824
	ds_read_b128 v[184:187], v217 offset:13856
	v_mfma_f32_32x32x16_bf16 v[64:79], v[152:155], v[92:95], v[64:79]
	ds_read_b128 v[204:207], v237 offset:57888
	ds_read_b128 v[192:195], v237 offset:62496
	s_waitcnt lgkmcnt(8)
	v_mfma_f32_32x32x16_bf16 v[64:79], v[156:159], v[96:99], v[64:79]
	ds_read_b128 v[168:171], v172 offset:8704
	ds_read_b128 v[160:163], v172 offset:8736
	v_mfma_f32_32x32x16_bf16 v[64:79], v[128:131], v[100:103], v[64:79]
	ds_read_b128 v[164:167], v172 offset:8768
	ds_read_b128 v[152:155], v172 offset:8800
	v_mfma_f32_32x32x16_bf16 v[64:79], v[132:135], v[104:107], v[64:79]
	ds_read_b128 v[156:159], v172 offset:8832
	ds_read_b128 v[128:131], v172 offset:8864
	v_mfma_f32_32x32x16_bf16 v[64:79], v[136:139], v[108:111], v[64:79]
	ds_read_b128 v[132:135], v172 offset:8896
	ds_read_b128 v[136:139], v172 offset:8928
	v_mfma_f32_32x32x16_bf16 v[64:79], v[140:143], v[112:115], v[64:79]
	ds_read_b128 v[140:143], v218 offset:22016
	ds_read_b128 v[172:175], v218 offset:22112
	v_mfma_f32_32x32x16_bf16 v[64:79], v[144:147], v[116:119], v[64:79]
	ds_read_b128 v[144:147], v218 offset:22048
	v_mfma_f32_32x32x16_bf16 v[64:79], v[148:151], v[120:123], v[64:79]
	ds_read_b128 v[148:151], v218 offset:22080
	v_mfma_f32_32x32x16_bf16 v[64:79], v[208:211], v[124:127], v[64:79]
	s_setprio 0
	s_barrier
	s_and_b64 vcc, exec, s[68:69]
	s_cbranch_vccnz .Ldmq_end
	s_cmp_ge_u32 s85, 4
	s_cbranch_scc1 .Lxdq_y
	s_and_b32 s99, s34, 1
	s_mul_i32 s98, s99, 0x4800
	s_addk_i32 s98, 0x6800
	s_mulk_i32 s99, 0x6800
	s_add_i32 s99, s99, s44
	s_add_i32 s98, s98, s44
	s_lshl_b32 s94, s34, 18
	s_lshl_b32 s90, s34, 13
	s_lshl_b32 s91, s34, 7
	s_add_i32 m0, s99, 0x0
	v_add_u32_e32 v255, s94, v221
	global_load_lds_dwordx4 v255, s[8:9]
	s_add_i32 m0, s99, 0x1000
	v_add_u32_e32 v255, s94, v222
	global_load_lds_dwordx4 v255, s[8:9]
	s_add_i32 m0, s99, 0x2000
	v_add_u32_e32 v255, s94, v223
	global_load_lds_dwordx4 v255, s[8:9]
	s_add_i32 m0, s99, 0x3000
	v_add_u32_e32 v255, s94, v224
	global_load_lds_dwordx4 v255, s[8:9]
	s_lshl_b32 s92, s34, s95
	s_add_i32 m0, s99, 0x4000
	v_add_u32_e32 v255, s92, v225
	global_load_lds_dwordx4 v255, s[46:47]
	s_add_i32 m0, s99, 0x5000
	v_add_u32_e32 v255, s90, v226
	global_load_lds_dwordx4 v255, s[52:53]
	s_branch .Ldmq_end

.LBB0_1283:
	v_exp_f32_e32 v64, v64
	v_exp_f32_e32 v65, v65
	v_exp_f32_e32 v66, v66
	v_exp_f32_e32 v67, v67
	v_exp_f32_e32 v68, v68
	v_add_f32_e32 v208, v64, v65
	v_exp_f32_e32 v69, v69
	v_exp_f32_e32 v70, v70
	v_add_f32_e32 v208, v66, v208
	v_exp_f32_e32 v71, v71
	v_add_f32_e32 v208, v67, v208
	v_exp_f32_e32 v72, v72
	v_add_f32_e32 v208, v68, v208
	v_exp_f32_e32 v73, v73
	v_add_f32_e32 v208, v69, v208
	v_exp_f32_e32 v74, v74
	v_add_f32_e32 v208, v70, v208
	v_exp_f32_e32 v75, v75
	v_add_f32_e32 v208, v71, v208
	v_exp_f32_e32 v76, v76
	v_add_f32_e32 v208, v72, v208
	v_exp_f32_e32 v77, v77
	v_add_f32_e32 v208, v73, v208
	v_exp_f32_e32 v78, v78
	v_add_f32_e32 v208, v74, v208
	v_exp_f32_e32 v79, v79
	v_add_f32_e32 v208, v75, v208
	v_add_f32_e32 v208, v76, v208
	v_add_f32_e32 v208, v77, v208
	v_add_f32_e32 v208, v78, v208
	v_add_f32_e32 v208, v79, v208
	v_add_f32_e32 v235, v235, v208
	v_cvt_pk_bf16_f32 v64, v64, v65
	v_cvt_pk_bf16_f32 v65, v66, v67
	v_cvt_pk_bf16_f32 v66, v68, v69
	v_cvt_pk_bf16_f32 v67, v70, v71
	v_cvt_pk_bf16_f32 v68, v72, v73
	v_cvt_pk_bf16_f32 v69, v74, v75
	v_cvt_pk_bf16_f32 v70, v76, v77
	v_cvt_pk_bf16_f32 v71, v78, v79
	s_barrier
	s_setprio 1
	s_waitcnt lgkmcnt(0)
	v_mfma_f32_32x32x16_bf16 v[48:63], v[180:183], v[64:67], v[48:63]
	v_mfma_f32_32x32x16_bf16 v[32:47], v[196:199], v[64:67], v[32:47]
	v_mfma_f32_32x32x16_bf16 v[16:31], v[188:191], v[64:67], v[16:31]
	v_mfma_f32_32x32x16_bf16 v[0:15], v[200:203], v[64:67], v[0:15]
	v_mfma_f32_32x32x16_bf16 v[48:63], v[176:179], v[68:71], v[48:63]
	v_mfma_f32_32x32x16_bf16 v[32:47], v[204:207], v[68:71], v[32:47]
	v_mfma_f32_32x32x16_bf16 v[16:31], v[192:195], v[68:71], v[16:31]
	v_mfma_f32_32x32x16_bf16 v[0:15], v[184:187], v[68:71], v[0:15]
	v_mfma_f32_32x32x16_bf16 v[64:79], v[168:171], v[80:83], v[238:253]
	ds_read_b128 v[180:183], v237 offset:53312
	v_mfma_f32_32x32x16_bf16 v[64:79], v[160:163], v[84:87], v[64:79]
	ds_read_b128 v[176:179], v237 offset:53344
	v_mfma_f32_32x32x16_bf16 v[64:79], v[164:167], v[88:91], v[64:79]
	ds_read_b128 v[184:187], v237 offset:57920
	v_mfma_f32_32x32x16_bf16 v[64:79], v[152:155], v[92:95], v[64:79]
	ds_read_b128 v[192:195], v237 offset:62528
	v_mfma_f32_32x32x16_bf16 v[64:79], v[156:159], v[96:99], v[64:79]
	ds_read_b128 v[196:199], v217 offset:13888
	v_mfma_f32_32x32x16_bf16 v[64:79], v[128:131], v[100:103], v[64:79]
	ds_read_b128 v[188:191], v217 offset:13920
	v_mfma_f32_32x32x16_bf16 v[64:79], v[132:135], v[104:107], v[64:79]
	ds_read_b128 v[200:203], v237 offset:57952
	v_mfma_f32_32x32x16_bf16 v[64:79], v[136:139], v[108:111], v[64:79]
	ds_read_b128 v[204:207], v237 offset:62560
	v_mfma_f32_32x32x16_bf16 v[64:79], v[140:143], v[112:115], v[64:79]
	v_mfma_f32_32x32x16_bf16 v[64:79], v[144:147], v[116:119], v[64:79]
	v_mfma_f32_32x32x16_bf16 v[64:79], v[148:151], v[120:123], v[64:79]
	v_mfma_f32_32x32x16_bf16 v[64:79], v[172:175], v[124:127], v[64:79]
	s_setprio 0
	s_waitcnt vmcnt(0) lgkmcnt(0)
	s_barrier
	s_add_i32 vcc_lo, s15, 63
	s_cmp_le_i32 vcc_lo, s86
	s_cbranch_scc1 .LBB0_1285
	v_add_u32_e32 v208, s15, v232
	v_add_u32_e32 v237, 32, v208
	v_cmp_lt_i32_e32 vcc, v237, v228
	s_nop 5
	v_cndmask_b32_e32 v65, v213, v65, vcc
	v_cmp_le_i32_e32 vcc, v237, v228
	v_add_u32_e32 v237, 34, v208
	s_nop 0
	v_cndmask_b32_e32 v64, v213, v64, vcc
	v_cmp_le_i32_e32 vcc, v237, v228
	v_add_u32_e32 v237, 35, v208
	s_nop 0
	v_cndmask_b32_e32 v66, v213, v66, vcc
	v_cmp_le_i32_e32 vcc, v237, v228
	v_add_u32_e32 v237, 40, v208
	s_nop 0
	v_cndmask_b32_e32 v67, v213, v67, vcc
	v_cmp_le_i32_e32 vcc, v237, v228
	v_add_u32_e32 v237, 41, v208
	s_nop 0
	v_cndmask_b32_e32 v68, v213, v68, vcc
	v_cmp_le_i32_e32 vcc, v237, v228
	v_add_u32_e32 v237, 42, v208
	s_nop 0
	v_cndmask_b32_e32 v69, v213, v69, vcc
	v_cmp_le_i32_e32 vcc, v237, v228
	v_add_u32_e32 v237, 43, v208
	s_nop 0
	v_cndmask_b32_e32 v70, v213, v70, vcc
	v_cmp_le_i32_e32 vcc, v237, v228
	v_add_u32_e32 v237, 48, v208
	s_nop 0
	v_cndmask_b32_e32 v71, v213, v71, vcc
	v_cmp_le_i32_e32 vcc, v237, v228
	v_add_u32_e32 v237, 49, v208
	s_nop 0
	v_cndmask_b32_e32 v72, v213, v72, vcc
	v_cmp_le_i32_e32 vcc, v237, v228
	v_add_u32_e32 v237, 50, v208
	s_nop 0
	v_cndmask_b32_e32 v73, v213, v73, vcc
	v_cmp_le_i32_e32 vcc, v237, v228
	v_add_u32_e32 v237, 51, v208
	s_nop 0
	v_cndmask_b32_e32 v74, v213, v74, vcc
	v_cmp_le_i32_e32 vcc, v237, v228
	v_add_u32_e32 v237, 56, v208
	s_nop 0
	v_cndmask_b32_e32 v75, v213, v75, vcc
	v_cmp_le_i32_e32 vcc, v237, v228
	v_add_u32_e32 v237, 57, v208
	s_nop 0
	v_cndmask_b32_e32 v76, v213, v76, vcc
	v_cmp_le_i32_e32 vcc, v237, v228
	v_add_u32_e32 v237, 58, v208
	v_add_u32_e32 v208, 59, v208
	v_cndmask_b32_e32 v77, v213, v77, vcc
	v_cmp_le_i32_e32 vcc, v237, v228
	s_nop 1
	v_cndmask_b32_e32 v78, v213, v78, vcc
	v_cmp_le_i32_e32 vcc, v208, v228
	s_nop 1
	v_cndmask_b32_e32 v79, v213, v79, vcc
